# on top of the residual-stream change: HGRN2 prompt recurrence compute waves fetch the output-gate rows and store the gated chunk outputs with dwordx4 + v_permlane32_swap pairs instead of four dwordx2
# speedup vs baseline: 1.0183x; 1.0087x over previous
.LBB0_984:
	v_readfirstlane_b32 s40, v134
	s_ashr_i32 s50, s40, 6
	s_ashr_i32 s57, s56, 31
	s_cmp_lt_i32 s50, 4
	s_mov_b64 s[40:41], -1
	s_barrier
	s_cbranch_scc0 .LBB0_992
	s_mul_hi_i32 s40, s56, 0x2aaaaaab
	s_lshr_b32 s41, s40, 31
	s_ashr_i32 s40, s40, 1
	s_add_i32 s41, s40, s41
	s_mul_i32 s40, s41, -12
	s_add_i32 s40, s40, s56
	s_load_dwordx2 s[62:63], s[46:47], 0x60
	s_load_dwordx2 s[60:61], s[46:47], 0xd0
	s_lshl_b32 s58, s40, 7
	s_lshl_b32 s40, s50, 5
	s_add_i32 s59, s40, s58
	s_waitcnt vmcnt(17)
	v_or_b32_e32 v2, s59, v138
	v_ashrrev_i32_e32 v3, 31, v2
	s_waitcnt lgkmcnt(0)
	v_lshl_add_u64 v[2:3], v[2:3], 2, s[62:63]
	global_load_dwordx4 v[94:97], v[2:3], off
	global_load_dwordx4 v[90:93], v[2:3], off offset:32
	global_load_dwordx4 v[86:89], v[2:3], off offset:64
	global_load_dwordx4 v[82:85], v[2:3], off offset:96
	s_waitcnt lgkmcnt(0)
	s_barrier
	ds_read_b128 v[2:5], v207 offset:8192
	s_waitcnt vmcnt(16)
	ds_read_b128 v[22:25], v207
	s_waitcnt vmcnt(14)
	ds_read_b128 v[26:29], v207 offset:9216
	ds_read_b128 v[30:33], v207 offset:1024
	s_waitcnt lgkmcnt(2)
	v_mfma_f32_32x32x16_bf16 v[6:21], v[2:5], v[22:25], 0
	s_ashr_i32 s59, s58, 31
	s_lshl_b32 s69, s41, 11
	s_lshl_b64 s[62:63], s[58:59], 1
	s_add_u32 s66, s60, s62
	s_addc_u32 s67, s61, s63
	s_ashr_i32 s41, s40, 31
	s_lshl_b64 s[64:65], s[40:41], 1
	s_waitcnt lgkmcnt(0)
	v_mfma_f32_32x32x16_bf16 v[6:21], v[26:29], v[30:33], v[6:21]
	ds_read_b128 v[2:5], v207 offset:10240
	ds_read_b128 v[26:29], v207 offset:2048
	s_waitcnt vmcnt(13)
	ds_read_b128 v[34:37], v207 offset:11264
	s_waitcnt vmcnt(11)
	ds_read_b128 v[38:41], v207 offset:3072
	s_add_u32 s66, s66, s64
	v_add_u32_e32 v194, 0, v139
	s_addc_u32 s67, s67, s65
	s_lshl_b32 s68, s50, 10
	v_add_u32_e32 v78, s68, v207
	v_lshlrev_b32_e32 v140, 1, v138
	s_waitcnt lgkmcnt(2)
	v_mfma_f32_32x32x16_bf16 v[6:21], v[2:5], v[26:29], v[6:21]
	ds_read_b128 v[2:5], v207 offset:13312
	s_waitcnt vmcnt(9)
	ds_read_b128 v[42:45], v207 offset:12288
	v_or_b32_e32 v181, s69, v136
	v_lshl_add_u32 v211, s50, 7, v135
	s_waitcnt lgkmcnt(2)
	v_mfma_f32_32x32x16_bf16 v[6:21], v[34:37], v[38:41], v[6:21]
	ds_read_b128 v[34:37], v207 offset:5120
	ds_read_b128 v[46:49], v207 offset:4096
	s_waitcnt lgkmcnt(0)
	v_mfma_f32_32x32x16_bf16 v[6:21], v[42:45], v[46:49], v[6:21]
	ds_read_b128 v[42:45], v207 offset:7168
	ds_read_b128 v[50:53], v207 offset:6144
	s_waitcnt vmcnt(8)
	ds_read_b128 v[54:57], v207 offset:15360
	s_waitcnt vmcnt(7)
	ds_read_b128 v[58:61], v207 offset:14336
	v_mfma_f32_32x32x16_bf16 v[6:21], v[2:5], v[34:37], v[6:21]
	ds_read_b128 v[2:5], v194 offset:33280
	s_waitcnt vmcnt(6)
	ds_read_b128 v[62:65], v194 offset:33312
	s_waitcnt vmcnt(4)
	ds_read_b128 v[70:73], v194 offset:33344
	ds_read_b128 v[74:77], v194 offset:33376
	ds_read_b128 v[66:69], v78 offset:24576
	ds_read_b128 v[98:101], v78 offset:28672
	s_waitcnt lgkmcnt(5)
	v_pk_mul_f32 v[2:3], v[2:3], 0 op_sel_hi:[1,0]
	s_waitcnt lgkmcnt(4)
	v_pk_mul_f32 v[62:63], v[62:63], 0 op_sel_hi:[1,0]
	v_pk_mul_f32 v[64:65], v[64:65], 0 op_sel_hi:[1,0]
	s_waitcnt lgkmcnt(3)
	v_pk_mul_f32 v[70:71], v[70:71], 0 op_sel_hi:[1,0]
	v_mfma_f32_32x32x16_bf16 v[6:21], v[58:61], v[50:53], v[6:21]
	v_mul_f32_e64 v60, v4, 0
	v_mul_f32_e64 v61, v5, 0
	v_cvt_pk_bf16_f32 v58, v2, v3
	v_mfma_f32_32x32x16_bf16 v[6:21], v[54:57], v[42:45], v[6:21]
	s_nop 11
	v_cndmask_b32_e64 v2, v6, 0, s[6:7]
	v_cndmask_b32_e64 v3, 0, v7, s[8:9]
	v_cndmask_b32_e64 v4, v8, 0, s[10:11]
	v_cndmask_b32_e64 v5, v9, 0, s[12:13]
	v_cndmask_b32_e64 v6, v10, 0, s[14:15]
	v_cndmask_b32_e64 v7, v11, 0, s[16:17]
	v_cndmask_b32_e64 v8, v12, 0, s[18:19]
	v_cndmask_b32_e64 v9, v13, 0, s[20:21]
	v_cvt_pk_bf16_f32 v2, v2, v3
	v_cvt_pk_bf16_f32 v3, v4, v5
	v_cvt_pk_bf16_f32 v4, v6, v7
	v_cvt_pk_bf16_f32 v5, v8, v9
	v_cndmask_b32_e64 v54, v14, 0, s[22:23]
	v_cndmask_b32_e64 v55, v15, 0, s[24:25]
	v_cndmask_b32_e64 v56, v16, 0, s[26:27]
	v_cndmask_b32_e64 v57, v17, 0, s[28:29]
	s_waitcnt lgkmcnt(1)
	v_mfma_f32_32x32x16_bf16 v[2:17], v[66:69], v[2:5], 0
	v_cndmask_b32_e64 v59, v18, 0, s[30:31]
	v_cndmask_b32_e64 v78, v19, 0, s[34:35]
	v_cndmask_b32_e64 v79, v20, 0, s[36:37]
	v_cndmask_b32_e64 v21, v21, 0, s[38:39]
	v_cvt_pk_bf16_f32 v18, v54, v55
	v_cvt_pk_bf16_f32 v19, v56, v57
	v_cvt_pk_bf16_f32 v20, v59, v78
	v_cvt_pk_bf16_f32 v21, v79, v21
	v_cvt_pk_bf16_f32 v59, v60, v61
	v_cvt_pk_bf16_f32 v60, v62, v63
	s_waitcnt lgkmcnt(0)
	v_mfma_f32_32x32x16_bf16 v[2:17], v[98:101], v[18:21], v[2:17]
	v_cvt_pk_bf16_f32 v61, v64, v65
	v_mul_f32_e64 v20, v72, 0
	v_mul_f32_e64 v21, v73, 0
	v_mul_f32_e64 v54, v74, 0
	v_mul_f32_e64 v55, v75, 0
	v_pk_mul_f32 v[56:57], v[76:77], 0 op_sel_hi:[1,0]
	v_cvt_pk_bf16_f32 v18, v70, v71
	v_cvt_pk_bf16_f32 v19, v20, v21
	v_cvt_pk_bf16_f32 v20, v54, v55
	v_mfma_f32_32x32x16_bf16 v[2:17], v[58:61], v[22:25], v[2:17]
	v_cvt_pk_bf16_f32 v21, v56, v57
	ds_read_b128 v[22:25], v194 offset:33408
	ds_read_b128 v[54:57], v194 offset:33440
	v_lshl_add_u64 v[58:59], s[66:67], 0, v[140:141]
	s_mov_b64 s[66:67], 0x1d403000
	v_lshl_add_u64 v[182:183], v[58:59], 0, s[66:67]
	v_mbcnt_lo_u32_b32 v165, -1, 0
	v_mbcnt_hi_u32_b32 v165, -1, v165
	v_and_b32_e32 v165, 32, v165
	v_lshrrev_b32_e32 v165, 2, v165
	v_mul_u32_u24_e32 v165, 3, v165
	v_sub_u32_e32 v165, 16, v165
	v_ashrrev_i32_e32 v167, 31, v165
	v_add_co_u32_e64 v182, s[100:101], v182, v165
	v_addc_co_u32_e64 v183, s[100:101], v183, v167, s[100:101]
	s_waitcnt lgkmcnt(0)
	v_pk_mul_f32 v[54:55], v[54:55], 0 op_sel_hi:[1,0]
	v_mfma_f32_32x32x16_bf16 v[2:17], v[18:21], v[30:33], v[2:17]
	v_mul_f32_e64 v30, v22, 0
	v_mul_f32_e64 v31, v23, 0
	v_mul_f32_e64 v32, v24, 0
	v_mul_f32_e64 v33, v25, 0
	ds_read_b128 v[18:21], v194 offset:33472
	ds_read_b128 v[22:25], v194 offset:33504
	v_pk_mul_f32 v[56:57], v[56:57], 0 op_sel_hi:[1,0]
	v_cvt_pk_bf16_f32 v30, v30, v31
	v_cvt_pk_bf16_f32 v31, v32, v33
	v_cvt_pk_bf16_f32 v32, v54, v55
	v_cvt_pk_bf16_f32 v33, v56, v57
	s_waitcnt lgkmcnt(1)
	v_pk_mul_f32 v[18:19], v[18:19], 0 op_sel_hi:[1,0]
	v_pk_mul_f32 v[20:21], v[20:21], 0 op_sel_hi:[1,0]
	s_waitcnt lgkmcnt(0)
	v_pk_mul_f32 v[22:23], v[22:23], 0 op_sel_hi:[1,0]
	v_mad_i64_i32 v[54:55], s[66:67], v181, s70, v[182:183]
	v_cvt_pk_bf16_f32 v18, v18, v19
	v_cvt_pk_bf16_f32 v19, v20, v21
	v_cvt_pk_bf16_f32 v20, v22, v23
	v_pk_mul_f32 v[22:23], v[24:25], 0 op_sel_hi:[1,0]
	v_mfma_f32_32x32x16_bf16 v[2:17], v[30:33], v[26:29], v[2:17]
	v_cvt_pk_bf16_f32 v21, v22, v23
	ds_read_b128 v[22:25], v194 offset:33536
	ds_read_b128 v[26:29], v194 offset:33568
	global_load_dwordx4 v[190:193], v[54:55], off
	global_load_dwordx4 v[184:187], v[54:55], off offset:32
	s_waitcnt lgkmcnt(1)
	v_pk_mul_f32 v[30:31], v[22:23], 0 op_sel_hi:[1,0]
	v_pk_mul_f32 v[32:33], v[24:25], 0 op_sel_hi:[1,0]
	v_mfma_f32_32x32x16_bf16 v[2:17], v[18:21], v[38:41], v[2:17]
	s_waitcnt lgkmcnt(0)
	v_mul_f32_e64 v38, v26, 0
	v_mul_f32_e64 v39, v27, 0
	v_mul_f32_e64 v40, v28, 0
	v_mul_f32_e64 v41, v29, 0
	v_cvt_pk_bf16_f32 v26, v30, v31
	v_cvt_pk_bf16_f32 v27, v32, v33
	v_cvt_pk_bf16_f32 v28, v38, v39
	v_cvt_pk_bf16_f32 v29, v40, v41
	ds_read_b128 v[18:21], v194 offset:33600
	ds_read_b128 v[22:25], v194 offset:33632
	v_mfma_f32_32x32x16_bf16 v[2:17], v[26:29], v[46:49], v[2:17]
	s_waitcnt lgkmcnt(1)
	v_mul_f32_e64 v18, v18, 0
	v_mul_f32_e64 v19, v19, 0
	v_mul_f32_e64 v20, v20, 0
	v_mul_f32_e64 v21, v21, 0
	s_waitcnt lgkmcnt(0)
	v_pk_mul_f32 v[22:23], v[22:23], 0 op_sel_hi:[1,0]
	v_cvt_pk_bf16_f32 v18, v18, v19
	v_cvt_pk_bf16_f32 v19, v20, v21
	v_cvt_pk_bf16_f32 v20, v22, v23
	v_pk_mul_f32 v[22:23], v[24:25], 0 op_sel_hi:[1,0]
	v_xor_b32_e32 v38, 32, v209
	v_cvt_pk_bf16_f32 v21, v22, v23
	ds_read_b128 v[22:25], v194 offset:33664
	ds_read_b128 v[26:29], v194 offset:33696
	v_mfma_f32_32x32x16_bf16 v[2:17], v[18:21], v[34:37], v[2:17]
	s_waitcnt lgkmcnt(1)
	v_mul_f32_e64 v30, v22, 0
	v_mul_f32_e64 v31, v23, 0
	v_mul_f32_e64 v32, v24, 0
	v_mul_f32_e64 v33, v25, 0
	s_waitcnt lgkmcnt(0)
	v_pk_mul_f32 v[34:35], v[26:27], 0 op_sel_hi:[1,0]
	v_pk_mul_f32 v[36:37], v[28:29], 0 op_sel_hi:[1,0]
	v_cvt_pk_bf16_f32 v26, v30, v31
	v_cvt_pk_bf16_f32 v27, v32, v33
	v_cvt_pk_bf16_f32 v28, v34, v35
	v_cvt_pk_bf16_f32 v29, v36, v37
	ds_read_b128 v[18:21], v194 offset:33728
	ds_read_b128 v[22:25], v194 offset:33760
	v_mfma_f32_32x32x16_bf16 v[2:17], v[26:29], v[50:53], v[2:17]
	s_waitcnt lgkmcnt(1)
	v_mul_f32_e64 v18, v18, 0
	v_mul_f32_e64 v19, v19, 0
	v_mul_f32_e64 v20, v20, 0
	v_mul_f32_e64 v21, v21, 0
	s_waitcnt lgkmcnt(0)
	v_pk_mul_f32 v[22:23], v[22:23], 0 op_sel_hi:[1,0]
	v_cvt_pk_bf16_f32 v18, v18, v19
	v_cvt_pk_bf16_f32 v19, v20, v21
	v_cvt_pk_bf16_f32 v20, v22, v23
	v_pk_mul_f32 v[22:23], v[24:25], 0 op_sel_hi:[1,0]
	v_and_b32_e32 v30, 64, v209
	v_cvt_pk_bf16_f32 v21, v22, v23
	v_add_u32_e32 v22, 64, v30
	v_cmp_lt_i32_e32 vcc, v38, v22
	v_mfma_f32_32x32x16_bf16 v[2:17], v[18:21], v[42:45], v[2:17]
	s_nop 0
	v_cndmask_b32_e32 v22, v209, v38, vcc
	v_lshlrev_b32_e32 v210, 2, v22
	s_nop 8
	v_mul_f32_e32 v18, v3, v3
	v_fmac_f32_e32 v18, v2, v2
	v_fmac_f32_e32 v18, v4, v4
	v_fmac_f32_e32 v18, v5, v5
	v_fmac_f32_e32 v18, v6, v6
	v_fmac_f32_e32 v18, v7, v7
	v_fmac_f32_e32 v18, v8, v8
	v_fmac_f32_e32 v18, v9, v9
	v_fmac_f32_e32 v18, v10, v10
	v_fmac_f32_e32 v18, v11, v11
	v_fmac_f32_e32 v18, v12, v12
	v_fmac_f32_e32 v18, v13, v13
	v_fmac_f32_e32 v18, v14, v14
	v_fmac_f32_e32 v18, v15, v15
	v_fmac_f32_e32 v18, v16, v16
	v_fmac_f32_e32 v18, v17, v17
	ds_bpermute_b32 v19, v210, v18
	s_and_saveexec_b64 s[66:67], s[4:5]
	s_cbranch_execz .LBB0_987
	s_waitcnt lgkmcnt(0)
	v_add_f32_e32 v18, v18, v19
	ds_write_b32 v211, v18
.LBB0_987:
	s_or_b64 exec, exec, s[66:67]
	s_waitcnt lgkmcnt(0)
	ds_read_b128 v[18:21], v207 offset:16384
	ds_read_b128 v[34:37], v207 offset:20480
	s_add_u32 s60, s60, 0x27683000
	s_addc_u32 s61, s61, 0
	s_add_u32 s62, s60, s62
	s_addc_u32 s63, s61, s63
	s_add_u32 s62, s62, s64
	s_addc_u32 s63, s63, s65
	s_mov_b32 s66, 1
	s_waitcnt lgkmcnt(1)
	v_mfma_f32_32x32x16_bf16 v[18:33], v[18:21], v[66:69], 0
	v_lshl_add_u64 v[188:189], s[62:63], 0, v[140:141]
	v_add_co_u32_e64 v188, s[100:101], v188, v165
	v_addc_co_u32_e64 v189, s[100:101], v189, v167, s[100:101]
	s_movk_i32 s64, 0x80
	s_waitcnt lgkmcnt(0)
	v_mfma_f32_32x32x16_bf16 v[18:33], v[34:37], v[98:101], v[18:33]
	ds_read_b128 v[102:105], v194 offset:32768
	ds_read_b128 v[106:109], v194 offset:32800
	ds_read_b128 v[110:113], v194 offset:32832
	ds_read_b128 v[114:117], v194 offset:32864
	ds_read_b128 v[34:37], v207 offset:17408
	ds_read_b128 v[50:53], v207 offset:21504
	s_waitcnt lgkmcnt(2)
	s_nop 4
	v_pk_fma_f32 v[116:117], v[116:117], 0, v[32:33] op_sel_hi:[1,0,1]
	s_waitcnt lgkmcnt(1)
	v_mfma_f32_32x32x16_bf16 v[34:49], v[34:37], v[66:69], 0
	v_fma_f32 v114, v114, 0, v30
	v_fma_f32 v115, v115, 0, v31
	v_fma_f32 v112, v112, 0, v28
	v_fma_f32 v113, v113, 0, v29
	v_fma_f32 v110, v110, 0, v26
	v_fma_f32 v111, v111, 0, v27
	v_pk_fma_f32 v[108:109], v[108:109], 0, v[24:25] op_sel_hi:[1,0,1]
	v_pk_fma_f32 v[106:107], v[106:107], 0, v[22:23] op_sel_hi:[1,0,1]
	v_pk_fma_f32 v[104:105], v[104:105], 0, v[20:21] op_sel_hi:[1,0,1]
	v_pk_fma_f32 v[102:103], v[102:103], 0, v[18:19] op_sel_hi:[1,0,1]
	s_waitcnt lgkmcnt(0)
	v_mfma_f32_32x32x16_bf16 v[34:49], v[50:53], v[98:101], v[34:49]
	ds_read_b128 v[118:121], v194 offset:32896
	ds_read_b128 v[122:125], v194 offset:32928
	ds_read_b128 v[126:129], v194 offset:32960
	ds_read_b128 v[130:133], v194 offset:32992
	ds_read_b128 v[50:53], v207 offset:18432
	ds_read_b128 v[70:73], v207 offset:22528
	s_waitcnt lgkmcnt(2)
	s_nop 4
	v_pk_fma_f32 v[132:133], v[132:133], 0, v[48:49] op_sel_hi:[1,0,1]
	s_waitcnt lgkmcnt(1)
	v_mfma_f32_32x32x16_bf16 v[50:65], v[50:53], v[66:69], 0
	v_fma_f32 v130, v130, 0, v46
	v_fma_f32 v131, v131, 0, v47
	v_fma_f32 v128, v128, 0, v44
	v_fma_f32 v129, v129, 0, v45
	v_fma_f32 v126, v126, 0, v42
	v_fma_f32 v127, v127, 0, v43
	v_pk_fma_f32 v[124:125], v[124:125], 0, v[40:41] op_sel_hi:[1,0,1]
	v_pk_fma_f32 v[122:123], v[122:123], 0, v[38:39] op_sel_hi:[1,0,1]
	v_pk_fma_f32 v[120:121], v[120:121], 0, v[36:37] op_sel_hi:[1,0,1]
	v_pk_fma_f32 v[118:119], v[118:119], 0, v[34:35] op_sel_hi:[1,0,1]
	s_waitcnt lgkmcnt(0)
	v_mfma_f32_32x32x16_bf16 v[50:65], v[70:73], v[98:101], v[50:65]
	ds_read_b128 v[196:199], v194 offset:33024
	ds_read_b128 v[212:215], v194 offset:33056
	ds_read_b128 v[216:219], v194 offset:33088
	ds_read_b128 v[220:223], v194 offset:33120
	ds_read_b128 v[70:73], v207 offset:19456
	ds_read_b128 v[238:241], v207 offset:23552
	s_waitcnt lgkmcnt(2)
	s_nop 4
	v_pk_fma_f32 v[64:65], v[222:223], 0, v[64:65] op_sel_hi:[1,0,1]
	s_waitcnt lgkmcnt(1)
	v_mfma_f32_32x32x16_bf16 v[66:81], v[70:73], v[66:69], 0
	v_fma_f32 v62, v220, 0, v62
	v_fma_f32 v63, v221, 0, v63
	v_fma_f32 v60, v218, 0, v60
	v_fma_f32 v61, v219, 0, v61
	v_fma_f32 v58, v216, 0, v58
	v_fma_f32 v59, v217, 0, v59
	v_pk_fma_f32 v[196:197], v[196:197], 0, v[50:51] op_sel_hi:[1,0,1]
	s_waitcnt lgkmcnt(0)
	v_mfma_f32_32x32x16_bf16 v[66:81], v[238:241], v[98:101], v[66:81]
	ds_read_b128 v[98:101], v194 offset:33152
	ds_read_b128 v[238:241], v194 offset:33184
	ds_read_b128 v[242:245], v194 offset:33216
	ds_read_b128 v[246:249], v194 offset:33248
	s_waitcnt lgkmcnt(0)
	s_barrier
	v_fma_f32 v194, v198, 0, v52
	v_fma_f32 v195, v199, 0, v53
	v_add_u32_e32 v198, s69, v136
	s_waitcnt lgkmcnt(0)
	s_nop 3
	v_pk_fma_f32 v[80:81], v[248:249], 0, v[80:81] op_sel_hi:[1,0,1]
	v_pk_fma_f32 v[78:79], v[246:247], 0, v[78:79] op_sel_hi:[1,0,1]
	v_pk_fma_f32 v[76:77], v[244:245], 0, v[76:77] op_sel_hi:[1,0,1]
	v_pk_fma_f32 v[74:75], v[242:243], 0, v[74:75] op_sel_hi:[1,0,1]
	v_pk_fma_f32 v[72:73], v[240:241], 0, v[72:73] op_sel_hi:[1,0,1]
	v_pk_fma_f32 v[70:71], v[238:239], 0, v[70:71] op_sel_hi:[1,0,1]
	v_pk_fma_f32 v[68:69], v[100:101], 0, v[68:69] op_sel_hi:[1,0,1]
	v_pk_fma_f32 v[66:67], v[98:99], 0, v[66:67] op_sel_hi:[1,0,1]
	v_pk_fma_f32 v[98:99], v[214:215], 0, v[56:57] op_sel_hi:[1,0,1]
	v_pk_fma_f32 v[100:101], v[212:213], 0, v[54:55] op_sel_hi:[1,0,1]
	s_branch .LBB0_989

.LBB0_989:
	s_waitcnt vmcnt(0)
	v_permlane32_swap_b32_e32 v190, v192
	v_permlane32_swap_b32_e32 v191, v193
	v_permlane32_swap_b32_e32 v184, v186
	v_permlane32_swap_b32_e32 v185, v187
	s_nop 1
	s_add_i32 s63, s64, 0xffffff80
	s_and_b32 s63, s63, 0x80
	v_lshl_add_u32 v20, s63, 2, v135
	ds_read2_b32 v[18:19], v20 offset1:32
	ds_read2_b32 v[20:21], v20 offset0:64 offset1:96
	s_mul_i32 s62, s66, 0xab
	s_bfe_u32 s62, s62, 0x70009
	s_mul_i32 s62, s62, 3
	s_waitcnt lgkmcnt(1)
	v_mov_b32_e32 v22, v18
	s_waitcnt lgkmcnt(0)
	v_mov_b32_e32 v23, v20
	v_mov_b32_e32 v20, v19
	v_pk_add_f32 v[18:19], v[22:23], v[20:21]
	s_sub_i32 s62, s66, s62
	v_add_f32_e32 v18, v18, v19
	v_fmamk_f32 v18, v18, 0x3c000000, v208
	v_mul_f32_e32 v19, 0x4b800000, v18
	v_cmp_gt_f32_e32 vcc, s71, v18
	v_ashrrev_i32_e32 v199, 31, v198
	s_and_b32 s62, s62, 0xff
	v_cndmask_b32_e32 v18, v18, v19, vcc
	v_rsq_f32_e32 v18, v18
	s_mul_i32 s62, s62, 0x8400
	s_add_i32 s62, s62, 0
	v_lshl_add_u32 v212, v137, 4, s62
	v_mul_f32_e32 v19, 0x45800000, v18
	v_cndmask_b32_e32 v50, v18, v19, vcc
	v_lshlrev_b64 v[18:19], 12, v[198:199]
	v_pk_mul_f32 v[2:3], v[2:3], v[50:51] op_sel_hi:[1,0]
	v_lshl_add_u64 v[200:201], v[188:189], 0, v[18:19]
	s_waitcnt vmcnt(7)
	v_pk_mul_f32 v[2:3], v[94:95], v[2:3]
	s_waitcnt vmcnt(3)
	v_lshlrev_b32_e32 v18, 16, v192
	v_and_b32_e32 v19, 0xffff0000, v192
	v_pk_mul_f32 v[2:3], v[2:3], v[18:19]
	ds_read_b128 v[214:217], v212
	v_cvt_pk_bf16_f32 v192, v2, v3
	v_pk_mul_f32 v[2:3], v[4:5], v[50:51] op_sel_hi:[1,0]
	v_lshlrev_b32_e32 v22, 16, v193
	v_pk_mul_f32 v[20:21], v[96:97], v[2:3]
	ds_read_b128 v[2:5], v212 offset:8192
	v_and_b32_e32 v23, 0xffff0000, v193
	v_pk_mul_f32 v[20:21], v[20:21], v[22:23]
	v_pk_mul_f32 v[12:13], v[12:13], v[50:51] op_sel_hi:[1,0]
	v_cvt_pk_bf16_f32 v193, v20, v21
	s_waitcnt lgkmcnt(0)
	v_mfma_f32_32x32x16_bf16 v[18:33], v[2:5], v[214:217], 0
	ds_read_b128 v[34:37], v212 offset:9216
	ds_read_b128 v[218:221], v212 offset:1024
	v_mul_f32_e64 v2, v6, v50
	v_mul_f32_e64 v3, v7, v50
	s_waitcnt vmcnt(3)
	v_lshlrev_b32_e32 v4, 16, v190
	v_pk_mul_f32 v[2:3], v[90:91], v[2:3]
	v_and_b32_e32 v5, 0xffff0000, v190
	v_pk_mul_f32 v[2:3], v[2:3], v[4:5]
	ds_read_b128 v[222:225], v212 offset:2048
	v_cvt_pk_bf16_f32 v190, v2, v3
	ds_read_b128 v[2:5], v212 offset:10240
	s_waitcnt lgkmcnt(2)
	v_mfma_f32_32x32x16_bf16 v[18:33], v[34:37], v[218:221], v[18:33]
	v_mul_f32_e64 v6, v8, v50
	v_mul_f32_e64 v7, v9, v50
	v_lshlrev_b32_e32 v36, 16, v191
	v_mul_f32_e64 v34, v92, v6
	v_mul_f32_e64 v35, v93, v7
	ds_read_b128 v[6:9], v212 offset:11264
	ds_read_b128 v[238:241], v212 offset:3072
	v_and_b32_e32 v37, 0xffff0000, v191
	ds_read_b128 v[46:49], v212 offset:4096
	v_add_u32_e32 v199, s62, v139
	s_waitcnt lgkmcnt(3)
	v_mfma_f32_32x32x16_bf16 v[18:33], v[2:5], v[222:225], v[18:33]
	v_mul_f32_e64 v2, v34, v36
	v_mul_f32_e64 v3, v35, v37
	s_waitcnt vmcnt(2)
	v_lshlrev_b32_e32 v34, 16, v186
	v_cvt_pk_bf16_f32 v191, v2, v3
	v_pk_mul_f32 v[2:3], v[10:11], v[50:51] op_sel_hi:[1,0]
	v_and_b32_e32 v35, 0xffff0000, v186
	v_pk_mul_f32 v[10:11], v[86:87], v[2:3]
	ds_read_b128 v[2:5], v212 offset:12288
	s_waitcnt lgkmcnt(2)
	v_mfma_f32_32x32x16_bf16 v[18:33], v[6:9], v[238:241], v[18:33]
	v_mul_f32_e64 v6, v10, v34
	v_mul_f32_e64 v7, v11, v35
	v_add_u32_e32 v198, 32, v198
	v_cvt_pk_bf16_f32 v186, v6, v7
	ds_read_b128 v[6:9], v212 offset:13312
	ds_read_b128 v[42:45], v212 offset:5120
	ds_read_b128 v[38:41], v212 offset:6144
	s_waitcnt lgkmcnt(3)
	v_mfma_f32_32x32x16_bf16 v[18:33], v[2:5], v[46:49], v[18:33]
	v_mul_f32_e64 v2, v88, v12
	v_mul_f32_e64 v3, v89, v13
	v_lshlrev_b32_e32 v4, 16, v187
	v_and_b32_e32 v5, 0xffff0000, v187
	v_mul_f32_e64 v2, v2, v4
	v_mul_f32_e64 v3, v3, v5
	s_waitcnt vmcnt(2)
	v_lshlrev_b32_e32 v12, 16, v184
	v_cvt_pk_bf16_f32 v187, v2, v3
	ds_read_b128 v[2:5], v212 offset:14336
	s_waitcnt lgkmcnt(2)
	v_mfma_f32_32x32x16_bf16 v[18:33], v[6:9], v[42:45], v[18:33]
	v_mul_f32_e64 v6, v14, v50
	v_mul_f32_e64 v7, v15, v50
	v_and_b32_e32 v13, 0xffff0000, v184
	v_mul_f32_e64 v10, v82, v6
	v_mul_f32_e64 v11, v83, v7
	ds_read_b128 v[6:9], v212 offset:15360
	ds_read_b128 v[34:37], v212 offset:7168
	s_waitcnt lgkmcnt(2)
	v_mfma_f32_32x32x16_bf16 v[18:33], v[2:5], v[38:41], v[18:33]
	v_mul_f32_e64 v2, v10, v12
	v_mul_f32_e64 v3, v11, v13
	v_add_u32_e32 v10, s68, v212
	ds_read_b128 v[54:57], v10 offset:24576
	v_cvt_pk_bf16_f32 v184, v2, v3
	v_pk_mul_f32 v[2:3], v[16:17], v[50:51] op_sel_hi:[1,0]
	v_lshlrev_b32_e32 v4, 16, v185
	v_pk_mul_f32 v[2:3], v[84:85], v[2:3]
	s_waitcnt lgkmcnt(1)
	v_mfma_f32_32x32x16_bf16 v[18:33], v[6:9], v[34:37], v[18:33]
	v_and_b32_e32 v5, 0xffff0000, v185
	v_mul_f32_e64 v165, v2, v4
	v_mul_f32_e64 v167, v3, v5
	ds_read_b128 v[50:53], v10 offset:28672
	v_cvt_pk_bf16_f32 v185, v165, v167
	s_nop 1
	v_permlane32_swap_b32_e32 v190, v192
	v_permlane32_swap_b32_e32 v191, v193
	v_permlane32_swap_b32_e32 v184, v186
	v_permlane32_swap_b32_e32 v185, v187
	global_store_dwordx4 v[200:201], v[190:193], off
	global_store_dwordx4 v[200:201], v[184:187], off offset:32
	s_nop 6
	v_cndmask_b32_e64 v2, v18, 0, s[6:7]
	v_cndmask_b32_e64 v3, 0, v19, s[8:9]
	v_cndmask_b32_e64 v4, v20, 0, s[10:11]
	v_cndmask_b32_e64 v5, v21, 0, s[12:13]
	v_cndmask_b32_e64 v6, v22, 0, s[14:15]
	v_cndmask_b32_e64 v7, v23, 0, s[16:17]
	v_cndmask_b32_e64 v8, v24, 0, s[18:19]
	v_cndmask_b32_e64 v9, v25, 0, s[20:21]
	v_cvt_pk_bf16_f32 v2, v2, v3
	v_cvt_pk_bf16_f32 v3, v4, v5
	v_cvt_pk_bf16_f32 v4, v6, v7
	v_cvt_pk_bf16_f32 v5, v8, v9
	v_cndmask_b32_e64 v18, v26, 0, s[22:23]
	v_cndmask_b32_e64 v19, v27, 0, s[24:25]
	s_waitcnt lgkmcnt(1)
	v_mfma_f32_32x32x16_bf16 v[2:17], v[54:57], v[2:5], 0
	v_cndmask_b32_e64 v20, v28, 0, s[26:27]
	v_cndmask_b32_e64 v21, v29, 0, s[28:29]
	v_cndmask_b32_e64 v26, v30, 0, s[30:31]
	v_cndmask_b32_e64 v27, v31, 0, s[34:35]
	v_cvt_pk_bf16_f32 v18, v18, v19
	v_cvt_pk_bf16_f32 v19, v20, v21
	ds_read_b128 v[22:25], v199 offset:33280
	v_cvt_pk_bf16_f32 v20, v26, v27
	ds_read_b128 v[26:29], v199 offset:33312
	v_cndmask_b32_e64 v30, v32, 0, s[36:37]
	v_cndmask_b32_e64 v31, v33, 0, s[38:39]
	v_cvt_pk_bf16_f32 v21, v30, v31
	s_waitcnt lgkmcnt(1)
	v_pk_mul_f32 v[30:31], v[102:103], v[22:23]
	v_pk_mul_f32 v[32:33], v[104:105], v[24:25]
	v_mfma_f32_32x32x16_bf16 v[2:17], v[50:53], v[18:21], v[2:17]
	s_waitcnt lgkmcnt(0)
	v_mul_f32_e64 v190, v106, v26
	v_mul_f32_e64 v191, v107, v27
	v_mul_f32_e64 v192, v108, v28
	v_mul_f32_e64 v193, v109, v29
	v_cvt_pk_bf16_f32 v26, v30, v31
	v_cvt_pk_bf16_f32 v27, v32, v33
	v_cvt_pk_bf16_f32 v28, v190, v191
	v_cvt_pk_bf16_f32 v29, v192, v193
	ds_read_b128 v[18:21], v199 offset:33344
	ds_read_b128 v[22:25], v199 offset:33376
	v_mfma_f32_32x32x16_bf16 v[2:17], v[26:29], v[214:217], v[2:17]
	s_waitcnt lgkmcnt(1)
	v_mul_f32_e64 v18, v110, v18
	v_mul_f32_e64 v19, v111, v19
	v_mul_f32_e64 v20, v112, v20
	v_mul_f32_e64 v21, v113, v21
	s_waitcnt lgkmcnt(0)
	v_pk_mul_f32 v[22:23], v[114:115], v[22:23]
	v_cvt_pk_bf16_f32 v18, v18, v19
	v_cvt_pk_bf16_f32 v19, v20, v21
	v_cvt_pk_bf16_f32 v20, v22, v23
	v_pk_mul_f32 v[22:23], v[116:117], v[24:25]
	ds_read_b128 v[26:29], v199 offset:33440
	v_cvt_pk_bf16_f32 v21, v22, v23
	ds_read_b128 v[22:25], v199 offset:33408
	v_mfma_f32_32x32x16_bf16 v[2:17], v[18:21], v[218:221], v[2:17]
	s_waitcnt lgkmcnt(0)
	v_mul_f32_e64 v30, v118, v22
	v_mul_f32_e64 v31, v119, v23
	v_mul_f32_e64 v32, v120, v24
	v_mul_f32_e64 v33, v121, v25
	ds_read_b128 v[18:21], v199 offset:33472
	ds_read_b128 v[22:25], v199 offset:33504
	v_pk_mul_f32 v[184:185], v[122:123], v[26:27]
	v_pk_mul_f32 v[186:187], v[124:125], v[28:29]
	v_cvt_pk_bf16_f32 v26, v30, v31
	v_cvt_pk_bf16_f32 v27, v32, v33
	v_cvt_pk_bf16_f32 v28, v184, v185
	v_cvt_pk_bf16_f32 v29, v186, v187
	s_waitcnt lgkmcnt(1)
	v_pk_mul_f32 v[18:19], v[126:127], v[18:19]
	v_pk_mul_f32 v[20:21], v[128:129], v[20:21]
	s_waitcnt lgkmcnt(0)
	v_pk_mul_f32 v[22:23], v[130:131], v[22:23]
	v_mad_i64_i32 v[30:31], s[62:63], v198, s70, v[182:183]
	v_cvt_pk_bf16_f32 v18, v18, v19
	v_cvt_pk_bf16_f32 v19, v20, v21
	v_cvt_pk_bf16_f32 v20, v22, v23
	v_pk_mul_f32 v[22:23], v[132:133], v[24:25]
	v_mfma_f32_32x32x16_bf16 v[2:17], v[26:29], v[222:225], v[2:17]
	v_cvt_pk_bf16_f32 v21, v22, v23
	ds_read_b128 v[22:25], v199 offset:33536
	ds_read_b128 v[26:29], v199 offset:33568
	global_load_dwordx4 v[190:193], v[30:31], off
	global_load_dwordx4 v[184:187], v[30:31], off offset:32
	s_waitcnt lgkmcnt(1)
	v_pk_mul_f32 v[30:31], v[196:197], v[22:23]
	v_pk_mul_f32 v[32:33], v[194:195], v[24:25]
	v_mfma_f32_32x32x16_bf16 v[2:17], v[18:21], v[238:241], v[2:17]
	s_waitcnt lgkmcnt(0)
	v_mul_f32_e64 v200, v100, v26
	v_mul_f32_e64 v201, v101, v27
	v_mul_f32_e64 v214, v98, v28
	v_mul_f32_e64 v215, v99, v29
	v_cvt_pk_bf16_f32 v26, v30, v31
	v_cvt_pk_bf16_f32 v27, v32, v33
	v_cvt_pk_bf16_f32 v28, v200, v201
	v_cvt_pk_bf16_f32 v29, v214, v215
	ds_read_b128 v[18:21], v199 offset:33600
	ds_read_b128 v[22:25], v199 offset:33632
	v_mfma_f32_32x32x16_bf16 v[2:17], v[26:29], v[46:49], v[2:17]
	s_waitcnt lgkmcnt(1)
	v_mul_f32_e64 v18, v58, v18
	v_mul_f32_e64 v19, v59, v19
	v_mul_f32_e64 v20, v60, v20
	v_mul_f32_e64 v21, v61, v21
	s_waitcnt lgkmcnt(0)
	v_pk_mul_f32 v[22:23], v[62:63], v[22:23]
	v_cvt_pk_bf16_f32 v18, v18, v19
	v_cvt_pk_bf16_f32 v19, v20, v21
	v_cvt_pk_bf16_f32 v20, v22, v23
	v_pk_mul_f32 v[22:23], v[64:65], v[24:25]
	s_nop 0
	v_cvt_pk_bf16_f32 v21, v22, v23
	ds_read_b128 v[22:25], v199 offset:33664
	ds_read_b128 v[26:29], v199 offset:33696
	v_mfma_f32_32x32x16_bf16 v[2:17], v[18:21], v[42:45], v[2:17]
	s_waitcnt lgkmcnt(1)
	v_mul_f32_e64 v30, v66, v22
	v_mul_f32_e64 v31, v67, v23
	v_mul_f32_e64 v32, v68, v24
	v_mul_f32_e64 v33, v69, v25
	s_waitcnt lgkmcnt(0)
	v_pk_mul_f32 v[42:43], v[70:71], v[26:27]
	v_pk_mul_f32 v[44:45], v[72:73], v[28:29]
	v_cvt_pk_bf16_f32 v26, v30, v31
	v_cvt_pk_bf16_f32 v27, v32, v33
	v_cvt_pk_bf16_f32 v28, v42, v43
	v_cvt_pk_bf16_f32 v29, v44, v45
	ds_read_b128 v[18:21], v199 offset:33728
	ds_read_b128 v[22:25], v199 offset:33760
	v_mfma_f32_32x32x16_bf16 v[2:17], v[26:29], v[38:41], v[2:17]
	s_waitcnt lgkmcnt(1)
	v_mul_f32_e64 v18, v74, v18
	v_mul_f32_e64 v19, v75, v19
	v_mul_f32_e64 v20, v76, v20
	v_mul_f32_e64 v21, v77, v21
	s_waitcnt lgkmcnt(0)
	v_pk_mul_f32 v[22:23], v[78:79], v[22:23]
	v_cvt_pk_bf16_f32 v18, v18, v19
	v_cvt_pk_bf16_f32 v19, v20, v21
	v_cvt_pk_bf16_f32 v20, v22, v23
	v_pk_mul_f32 v[22:23], v[80:81], v[24:25]
	s_nop 0
	v_cvt_pk_bf16_f32 v21, v22, v23
	s_nop 1
	v_mfma_f32_32x32x16_bf16 v[2:17], v[18:21], v[34:37], v[2:17]
	s_nop 11
	v_mul_f32_e32 v18, v3, v3
	v_fmac_f32_e32 v18, v2, v2
	v_fmac_f32_e32 v18, v4, v4
	v_fmac_f32_e32 v18, v5, v5
	v_fmac_f32_e32 v18, v6, v6
	v_fmac_f32_e32 v18, v7, v7
	v_fmac_f32_e32 v18, v8, v8
	v_fmac_f32_e32 v18, v9, v9
	v_fmac_f32_e32 v18, v10, v10
	v_fmac_f32_e32 v18, v11, v11
	v_fmac_f32_e32 v18, v12, v12
	v_fmac_f32_e32 v18, v13, v13
	v_fmac_f32_e32 v18, v14, v14
	v_fmac_f32_e32 v18, v15, v15
	v_fmac_f32_e32 v18, v16, v16
	v_fmac_f32_e32 v18, v17, v17
	ds_bpermute_b32 v19, v210, v18
	s_and_saveexec_b64 s[62:63], s[4:5]
	s_cbranch_execz .LBB0_988
	s_and_b32 s65, s64, 0x80
	s_waitcnt lgkmcnt(0)
	v_add_f32_e32 v18, v18, v19
	v_lshl_add_u32 v19, s65, 2, v211
	ds_write_b32 v19, v18
	s_branch .LBB0_988
.LBB0_991:
	s_waitcnt vmcnt(0)
	v_permlane32_swap_b32_e32 v190, v192
	v_permlane32_swap_b32_e32 v191, v193
	v_permlane32_swap_b32_e32 v184, v186
	v_permlane32_swap_b32_e32 v185, v187
	s_nop 1
	ds_read2_b32 v[18:19], v163 offset1:32
	ds_read2_b32 v[20:21], v163 offset0:64 offset1:96
	s_waitcnt lgkmcnt(1)
	v_mov_b32_e32 v22, v18
	s_waitcnt lgkmcnt(0)
	v_mov_b32_e32 v23, v20
	v_mov_b32_e32 v20, v19
	v_pk_add_f32 v[18:19], v[22:23], v[20:21]
	s_waitcnt vmcnt(3)
	v_lshlrev_b32_e32 v22, 16, v192
	v_add_f32_e32 v18, v18, v19
	v_fmamk_f32 v18, v18, 0x3c000000, v208
	v_mul_f32_e32 v19, 0x4b800000, v18
	v_cmp_gt_f32_e32 vcc, s71, v18
	v_and_b32_e32 v23, 0xffff0000, v192
	s_nop 0
	v_cndmask_b32_e32 v18, v18, v19, vcc
	v_rsq_f32_e32 v20, v18
	v_or_b32_e32 v18, 0x7e0, v181
	v_ashrrev_i32_e32 v19, 31, v18
	v_lshlrev_b64 v[18:19], 12, v[18:19]
	v_mul_f32_e32 v21, 0x45800000, v20
	v_cndmask_b32_e32 v20, v20, v21, vcc
	v_pk_mul_f32 v[2:3], v[2:3], v[20:21] op_sel_hi:[1,0]
	v_lshl_add_u64 v[18:19], s[60:61], 0, v[18:19]
	v_pk_mul_f32 v[2:3], v[94:95], v[2:3]
	v_pk_mul_f32 v[4:5], v[4:5], v[20:21] op_sel_hi:[1,0]
	v_lshl_add_u64 v[18:19], s[58:59], 1, v[18:19]
	v_pk_mul_f32 v[2:3], v[2:3], v[22:23]
	v_pk_mul_f32 v[4:5], v[96:97], v[4:5]
	v_lshlrev_b32_e32 v22, 16, v193
	v_and_b32_e32 v23, 0xffff0000, v193
	v_lshl_add_u64 v[18:19], s[40:41], 1, v[18:19]
	v_pk_mul_f32 v[4:5], v[4:5], v[22:23]
	v_lshl_add_u64 v[18:19], v[18:19], 0, v[140:141]
	v_cvt_pk_bf16_f32 v2, v2, v3
	v_cvt_pk_bf16_f32 v3, v4, v5
	global_store_dwordx2 v[18:19], v[2:3], off
	v_pk_mul_f32 v[2:3], v[6:7], v[20:21] op_sel_hi:[1,0]
	s_waitcnt vmcnt(3)
	v_lshlrev_b32_e32 v4, 16, v190
	v_pk_mul_f32 v[2:3], v[90:91], v[2:3]
	v_and_b32_e32 v5, 0xffff0000, v190
	v_pk_mul_f32 v[2:3], v[2:3], v[4:5]
	v_pk_mul_f32 v[4:5], v[8:9], v[20:21] op_sel_hi:[1,0]
	v_lshlrev_b32_e32 v6, 16, v191
	v_pk_mul_f32 v[4:5], v[92:93], v[4:5]
	v_and_b32_e32 v7, 0xffff0000, v191
	v_pk_mul_f32 v[4:5], v[4:5], v[6:7]
	v_cvt_pk_bf16_f32 v2, v2, v3
	v_cvt_pk_bf16_f32 v3, v4, v5
	global_store_dwordx2 v[18:19], v[2:3], off offset:16
	v_pk_mul_f32 v[2:3], v[10:11], v[20:21] op_sel_hi:[1,0]
	s_waitcnt vmcnt(3)
	v_lshlrev_b32_e32 v4, 16, v186
	v_pk_mul_f32 v[2:3], v[86:87], v[2:3]
	v_and_b32_e32 v5, 0xffff0000, v186
	v_pk_mul_f32 v[2:3], v[2:3], v[4:5]
	v_pk_mul_f32 v[4:5], v[12:13], v[20:21] op_sel_hi:[1,0]
	v_lshlrev_b32_e32 v6, 16, v187
	v_pk_mul_f32 v[4:5], v[88:89], v[4:5]
	v_and_b32_e32 v7, 0xffff0000, v187
	v_pk_mul_f32 v[4:5], v[4:5], v[6:7]
	v_cvt_pk_bf16_f32 v2, v2, v3
	v_cvt_pk_bf16_f32 v3, v4, v5
	global_store_dwordx2 v[18:19], v[2:3], off offset:32
	v_pk_mul_f32 v[2:3], v[14:15], v[20:21] op_sel_hi:[1,0]
	s_waitcnt vmcnt(3)
	v_lshlrev_b32_e32 v4, 16, v184
	v_pk_mul_f32 v[2:3], v[82:83], v[2:3]
	v_and_b32_e32 v5, 0xffff0000, v184
	v_pk_mul_f32 v[2:3], v[2:3], v[4:5]
	v_pk_mul_f32 v[4:5], v[16:17], v[20:21] op_sel_hi:[1,0]
	v_lshlrev_b32_e32 v6, 16, v185
	v_pk_mul_f32 v[4:5], v[84:85], v[4:5]
	v_and_b32_e32 v7, 0xffff0000, v185
	v_pk_mul_f32 v[4:5], v[4:5], v[6:7]
	v_cvt_pk_bf16_f32 v2, v2, v3
	v_cvt_pk_bf16_f32 v3, v4, v5
	global_store_dwordx2 v[18:19], v[2:3], off offset:48
	s_load_dwordx2 s[58:59], s[46:47], 0xc8
	s_lshl_b64 s[60:61], s[56:57], 16
	v_lshlrev_b32_e32 v140, 2, v136
	s_waitcnt lgkmcnt(0)
	s_add_u32 s58, s58, s60
	s_addc_u32 s59, s59, s61
	s_lshl_b64 s[40:41], s[40:41], 2
	s_add_u32 s40, s58, s40
	s_addc_u32 s41, s59, s41
	v_lshl_add_u64 v[2:3], s[40:41], 0, v[140:141]
	v_lshl_add_u64 v[2:3], v[2:3], 0, s[52:53]
	v_lshl_add_u64 v[4:5], v[2:3], 0, v[142:143]
	v_lshl_add_u64 v[6:7], v[2:3], 0, v[144:145]
	global_store_dword v[4:5], v102, off
	global_store_dword v[4:5], v103, off offset:512
	global_store_dword v[6:7], v104, off
	v_lshl_add_u64 v[6:7], v[2:3], 0, v[146:147]
	global_store_dword v[6:7], v105, off
	v_lshl_add_u64 v[6:7], v[2:3], 0, v[148:149]
	global_store_dword v[6:7], v106, off
	v_lshl_add_u64 v[6:7], v[2:3], 0, v[150:151]
	global_store_dword v[6:7], v107, off
	v_lshl_add_u64 v[6:7], v[2:3], 0, v[152:153]
	global_store_dword v[6:7], v108, off
	v_lshl_add_u64 v[6:7], v[2:3], 0, v[154:155]
	global_store_dword v[6:7], v109, off
	v_lshl_add_u64 v[6:7], v[2:3], 0, v[156:157]
	global_store_dword v[6:7], v110, off
	v_lshl_add_u64 v[6:7], v[2:3], 0, v[158:159]
	global_store_dword v[6:7], v111, off
	v_lshl_add_u64 v[6:7], v[2:3], 0, v[160:161]
	global_store_dword v[6:7], v112, off
	v_lshl_add_u64 v[6:7], v[2:3], 0, v[170:171]
	global_store_dword v[6:7], v113, off
	v_lshl_add_u64 v[6:7], v[2:3], 0, v[172:173]
	global_store_dword v[6:7], v114, off
	v_lshl_add_u64 v[6:7], v[2:3], 0, v[174:175]
	global_store_dword v[6:7], v115, off
	v_lshl_add_u64 v[6:7], v[2:3], 0, v[176:177]
	v_lshl_add_u64 v[2:3], v[2:3], 0, v[178:179]
	global_store_dword v[2:3], v117, off
	v_add_co_u32_e32 v2, vcc, s72, v4
	global_store_dword v[6:7], v116, off
	s_nop 0
	v_addc_co_u32_e32 v3, vcc, 0, v5, vcc
	v_add_co_u32_e32 v6, vcc, s73, v4
	s_mov_b64 s[40:41], 0
	s_nop 0
	v_addc_co_u32_e32 v7, vcc, 0, v5, vcc
	global_store_dword v[6:7], v118, off offset:-4096
	global_store_dword v[2:3], v119, off offset:512
	global_store_dword v[2:3], v120, off offset:1024
	global_store_dword v[2:3], v121, off offset:1536
	global_store_dword v[6:7], v122, off
	global_store_dword v[6:7], v123, off offset:512
	global_store_dword v[6:7], v124, off offset:1024
	global_store_dword v[6:7], v125, off offset:1536
	v_add_co_u32_e32 v2, vcc, s74, v4
	s_nop 1
	v_addc_co_u32_e32 v3, vcc, 0, v5, vcc
	v_add_co_u32_e32 v6, vcc, s75, v4
	s_nop 1
	v_addc_co_u32_e32 v7, vcc, 0, v5, vcc
	global_store_dword v[6:7], v126, off offset:-4096
	global_store_dword v[2:3], v127, off offset:512
	global_store_dword v[2:3], v128, off offset:1024
	global_store_dword v[2:3], v129, off offset:1536
	global_store_dword v[6:7], v130, off
	global_store_dword v[6:7], v131, off offset:512
	global_store_dword v[6:7], v132, off offset:1024
	global_store_dword v[6:7], v133, off offset:1536
	v_add_co_u32_e32 v2, vcc, s76, v4
	s_nop 1
	v_addc_co_u32_e32 v3, vcc, 0, v5, vcc
	v_add_co_u32_e32 v6, vcc, s77, v4
	s_nop 1
	v_addc_co_u32_e32 v7, vcc, 0, v5, vcc
	global_store_dword v[6:7], v196, off offset:-4096
	global_store_dword v[2:3], v197, off offset:512
	global_store_dword v[2:3], v194, off offset:1024
	global_store_dword v[2:3], v195, off offset:1536
	global_store_dword v[6:7], v100, off
	global_store_dword v[6:7], v101, off offset:512
	global_store_dword v[6:7], v98, off offset:1024
	global_store_dword v[6:7], v99, off offset:1536
	v_add_co_u32_e32 v2, vcc, s78, v4
	s_nop 1
	v_addc_co_u32_e32 v3, vcc, 0, v5, vcc
	v_add_co_u32_e32 v6, vcc, s79, v4
	s_nop 1
	v_addc_co_u32_e32 v7, vcc, 0, v5, vcc
	global_store_dword v[6:7], v58, off offset:-4096
	global_store_dword v[2:3], v59, off offset:512
	global_store_dword v[2:3], v60, off offset:1024
	global_store_dword v[2:3], v61, off offset:1536
	global_store_dword v[6:7], v62, off
	global_store_dword v[6:7], v63, off offset:512
	global_store_dword v[6:7], v64, off offset:1024
	global_store_dword v[6:7], v65, off offset:1536
	v_add_co_u32_e32 v2, vcc, s82, v4
	s_nop 1
	v_addc_co_u32_e32 v3, vcc, 0, v5, vcc
	v_add_co_u32_e32 v6, vcc, s83, v4
	s_nop 1
	v_addc_co_u32_e32 v7, vcc, 0, v5, vcc
	global_store_dword v[6:7], v66, off offset:-4096
	global_store_dword v[2:3], v67, off offset:512
	global_store_dword v[2:3], v68, off offset:1024
	global_store_dword v[2:3], v69, off offset:1536
	global_store_dword v[6:7], v70, off
	global_store_dword v[6:7], v71, off offset:512
	global_store_dword v[6:7], v72, off offset:1024
	global_store_dword v[6:7], v73, off offset:1536
	v_add_co_u32_e32 v2, vcc, s84, v4
	s_nop 1
	v_addc_co_u32_e32 v3, vcc, 0, v5, vcc
	global_store_dword v[2:3], v74, off
	global_store_dword v[2:3], v75, off offset:512
	global_store_dword v[2:3], v76, off offset:1024
	global_store_dword v[2:3], v77, off offset:1536
	v_add_co_u32_e32 v2, vcc, 0xf000, v4
	s_nop 1
	v_addc_co_u32_e32 v3, vcc, 0, v5, vcc
	global_store_dword v[2:3], v78, off
	global_store_dword v[2:3], v79, off offset:512
	global_store_dword v[2:3], v80, off offset:1024
	global_store_dword v[2:3], v81, off offset:1536
